# v164 + phase C Fourier items dealt so the eight workgroups writing the eight 16-byte pieces of one D1 cache line share an XCD (their partial writes merge in one L2)
# speedup vs baseline: 1.0229x; 1.0042x over previous
.LBB0_576:
	s_andn2_b64 vcc, exec, s[12:13]
	s_cbranch_vccnz .LBB0_578
	s_and_b32 s88, s22, 31
	s_lshl_b32 s88, s88, 3
	s_lshr_b32 s16, s22, 5
	s_or_b32 s88, s88, s16
	s_cmpk_eq_i32 s23, 0x100
	s_cselect_b32 s88, s88, s22
	s_ashr_i32 s16, s88, 7
	s_and_b32 s12, s88, 15
	s_lshl_b32 s17, s16, 13
	s_lshl_b32 s18, s12, 9
	s_lshr_b32 s13, s88, 4
	s_or_b32 s17, s17, s18
	s_lshl_b32 s12, s12, 3
	s_movk_i32 s28, 0x1000
	s_branch .LBB0_579
